# attn_backedge
# speedup vs baseline: 1.0004x; 1.0004x over previous
; #define SBAR() __builtin_amdgcn_sched_barrier(0)
; #define SLOAD(i, k0) do { sr_[i].vs0 = *reinterpret_cast<const bf16x8*>(&Vh[(long)((k0) + sr) * LDK + sc]); sr_[i].vs1 = *reinterpret_cast<const bf16x8*>(&Vh[(long)((k0) + 32 + sr) * LDK + sc]); \
;     sr_[i].ks0 = *reinterpret_cast<const bf16x8*>(&Kh[(long)((k0) + sr) * LDK + sc]); sr_[i].ks1 = *reinterpret_cast<const bf16x8*>(&Kh[(long)((k0) + 32 + sr) * LDK + sc]); } while (0)
; __device__ __forceinline__ void finishSM(f32x16& p0, f32x16& p1, float alpha, float& l_reg, bf16x8& pa0, bf16x8& pa1, bf16x8& pa2, bf16x8& pa3) {
; #pragma unroll
;   for (int r = 0; r < 16; ++r) p1[r] = __builtin_amdgcn_exp2f(p1[r]);
;   float ps = 0;
; #pragma unroll
;   for (int r = 0; r < 16; ++r) ps += p0[r];
; #pragma unroll
;   for (int r = 0; r < 16; ++r) ps += p1[r];
;   { auto rr = __builtin_amdgcn_permlane32_swap(__float_as_uint(ps), __float_as_uint(ps), false, false);
;     ps = __uint_as_float(rr[0]) + __uint_as_float(rr[1]); }
;   l_reg = l_reg * alpha + ps;
;     ...
;   PK4(p0, 0, pa0); PK4(p0, 8, pa1); PK4(p1, 0, pa2); PK4(p1, 8, pa3);
;     ...
; }
; __device__ __forceinline__ void qkt(f32x16& p0, f32x16& p1, const u16* Ks, const bf16x8* qr, int r32, int hi) {
;   p0 = f32x16{}; p1 = f32x16{};
; #pragma unroll
;   for (int d0 = 0; d0 < 8; ++d0) { int cb = (d0 * 16 + hi * 8) * 2;
;     bf16x8 b0 = *reinterpret_cast<const bf16x8*>((const char*)Ks + KSWZ(r32, cb));
;     bf16x8 b1 = *reinterpret_cast<const bf16x8*>((const char*)Ks + KSWZ(32 + r32, cb));
;     p0 = __builtin_amdgcn_mfma_f32_32x32x16_bf16(b0, qr[d0], p0, 0, 0, 0);
;     p1 = __builtin_amdgcn_mfma_f32_32x32x16_bf16(b1, qr[d0], p1, 0, 0, 0); }
; }
; template <bool BAND>
; __device__ __forceinline__ void attn_body(const u16* Qb, const u16* __restrict__ Kh, const u16* __restrict__ Vh, u16* Ob, int NT, int kpos0, int qpos0, float sink_l2, char* lds, const float* __restrict__ qn) {
;     ...
;     SBAR(); qkt(pB0, pB1, (u16*)((char*)K_lds + SHM_K), qr, r32, hi);
;     finishSM(pA0, pA1, alA, l_reg, pa0, pa1, pa2, pa3); SBAR();
;     SLOAD(SO, (j + SDEPTH) * KVBLK); SBAR();
;     pv_d0(o, vb0, pa0, pa1, pa2, pa3); partialSM<BAND>(pB0, pB1, m_reg, mnB, alB, dq + j * KVBLK);
.LBB0_1644:
	s_barrier
	ds_read_b128 v[64:67], v189 offset:49152
	ds_read_b128 v[68:71], v189 offset:57344
	ds_read_b128 v[206:209], v192 offset:49152
	ds_read_b128 v[210:213], v192 offset:57344
	v_add_f32_e32 v160, 0, v161
	v_add_f32_e32 v160, v175, v160
	s_waitcnt lgkmcnt(3)
	v_mfma_f32_32x32x16_bf16 v[80:95], v[64:67], v[124:127], 0
	v_add_f32_e32 v160, v162, v160
	v_add_f32_e32 v160, v201, v160
	v_add_f32_e32 v160, v174, v160
	v_add_f32_e32 v160, v204, v160
	v_add_f32_e32 v160, v163, v160
	v_add_f32_e32 v160, v173, v160
	v_add_f32_e32 v160, v164, v160
	s_waitcnt lgkmcnt(2)
	v_mfma_f32_32x32x16_bf16 v[64:79], v[68:71], v[124:127], 0
	v_add_f32_e32 v160, v171, v160
	v_add_f32_e32 v160, v165, v160
	v_add_f32_e32 v160, v172, v160
	v_exp_f32_e32 v158, v158
	v_add_f32_e32 v160, v166, v160
	v_exp_f32_e32 v159, v159
	v_add_f32_e32 v160, v169, v160
	s_waitcnt lgkmcnt(1)
	v_mfma_f32_32x32x16_bf16 v[80:95], v[206:209], v[120:123], v[80:95]
	v_exp_f32_e32 v156, v156
	v_add_f32_e32 v160, v167, v160
	v_exp_f32_e32 v157, v157
	v_add_f32_e32 v160, v170, v160
	v_exp_f32_e32 v152, v152
	v_add_f32_e32 v160, v158, v160
	v_exp_f32_e32 v153, v153
	s_waitcnt lgkmcnt(0)
	v_mfma_f32_32x32x16_bf16 v[64:79], v[210:213], v[120:123], v[64:79]
	ds_read_b128 v[206:209], v193 offset:49152
	ds_read_b128 v[210:213], v193 offset:57344
	v_add_f32_e32 v160, v159, v160
	v_exp_f32_e32 v148, v148
	v_add_f32_e32 v160, v156, v160
	v_exp_f32_e32 v149, v149
	v_add_f32_e32 v160, v157, v160
	v_exp_f32_e32 v144, v144
	s_waitcnt lgkmcnt(1)
	v_mfma_f32_32x32x16_bf16 v[80:95], v[206:209], v[116:119], v[80:95]
	v_add_f32_e32 v160, v152, v160
	v_exp_f32_e32 v145, v145
	v_add_f32_e32 v160, v153, v160
	v_exp_f32_e32 v154, v154
	v_add_f32_e32 v160, v148, v160
	v_exp_f32_e32 v155, v155
	v_add_f32_e32 v160, v149, v160
	s_waitcnt lgkmcnt(0)
	v_mfma_f32_32x32x16_bf16 v[64:79], v[210:213], v[116:119], v[64:79]
	ds_read_b128 v[206:209], v190 offset:49152
	ds_read_b128 v[210:213], v190 offset:57344
	v_exp_f32_e32 v150, v150
	v_add_f32_e32 v160, v144, v160
	v_exp_f32_e32 v151, v151
	v_add_f32_e32 v160, v145, v160
	v_exp_f32_e32 v146, v146
	v_add_f32_e32 v160, v154, v160
	s_waitcnt lgkmcnt(1)
	v_mfma_f32_32x32x16_bf16 v[80:95], v[206:209], v[112:115], v[80:95]
	v_exp_f32_e32 v147, v147
	v_add_f32_e32 v160, v155, v160
	v_add_f32_e32 v160, v150, v160
	v_add_f32_e32 v160, v151, v160
	v_add_f32_e32 v160, v146, v160
	v_add_f32_e32 v198, v147, v160
	v_mov_b32_e32 v199, v198
	s_waitcnt lgkmcnt(0)
	v_mfma_f32_32x32x16_bf16 v[64:79], v[210:213], v[112:115], v[64:79]
	ds_read_b128 v[206:209], v191 offset:49152
	ds_read_b128 v[210:213], v191 offset:57344
	v_permlane32_swap_b32_e32 v198, v199
	s_waitcnt lgkmcnt(1)
	v_mfma_f32_32x32x16_bf16 v[80:95], v[206:209], v[108:111], v[80:95]
	s_waitcnt lgkmcnt(0)
	v_mfma_f32_32x32x16_bf16 v[64:79], v[210:213], v[108:111], v[64:79]
	ds_read_b128 v[206:209], v194 offset:49152
	ds_read_b128 v[210:213], v194 offset:57344
	s_waitcnt lgkmcnt(1)
	v_mfma_f32_32x32x16_bf16 v[80:95], v[206:209], v[104:107], v[80:95]
	s_waitcnt lgkmcnt(0)
	v_mfma_f32_32x32x16_bf16 v[64:79], v[210:213], v[104:107], v[64:79]
	ds_read_b128 v[206:209], v195 offset:49152
	ds_read_b128 v[210:213], v195 offset:57344
	s_waitcnt lgkmcnt(1)
	v_mfma_f32_32x32x16_bf16 v[80:95], v[206:209], v[100:103], v[80:95]
	s_waitcnt lgkmcnt(0)
	v_mfma_f32_32x32x16_bf16 v[64:79], v[210:213], v[100:103], v[64:79]
	ds_read_b128 v[206:209], v196 offset:49152
	ds_read_b128 v[210:213], v196 offset:57344
	v_cvt_pk_bf16_f32 v160, v161, v175
	v_cvt_pk_bf16_f32 v161, v162, v201
	v_cvt_pk_bf16_f32 v162, v174, v204
	v_cvt_pk_bf16_f32 v163, v163, v173
	v_cvt_pk_bf16_f32 v164, v164, v171
	v_cvt_pk_bf16_f32 v165, v165, v172
	s_waitcnt lgkmcnt(1)
	v_mfma_f32_32x32x16_bf16 v[80:95], v[206:209], v[96:99], v[80:95]
	v_cvt_pk_bf16_f32 v166, v166, v169
	v_cvt_pk_bf16_f32 v167, v167, v170
	v_cvt_pk_bf16_f32 v170, v158, v159
	v_cvt_pk_bf16_f32 v171, v156, v157
	v_cvt_pk_bf16_f32 v172, v152, v153
	v_cvt_pk_bf16_f32 v173, v148, v149
	v_cvt_pk_bf16_f32 v200, v144, v145
	s_waitcnt lgkmcnt(0)
	v_mfma_f32_32x32x16_bf16 v[64:79], v[210:213], v[96:99], v[64:79]
	v_cvt_pk_bf16_f32 v201, v154, v155
	v_cvt_pk_bf16_f32 v202, v150, v151
	v_permlane32_swap_b32_e32 v160, v162
	v_cvt_pk_bf16_f32 v203, v146, v147
	v_permlane32_swap_b32_e32 v200, v202
	v_permlane32_swap_b32_e32 v161, v163
	v_permlane32_swap_b32_e32 v164, v166
	v_permlane32_swap_b32_e32 v165, v167
	v_permlane32_swap_b32_e32 v170, v172
	v_permlane32_swap_b32_e32 v171, v173
	v_permlane32_swap_b32_e32 v201, v203
	s_mov_b32 s8, 0xffff4000
	v_add_co_u32_e32 v144, vcc, s8, v178
	s_movk_i32 s8, 0x8000
	s_nop 0
	v_addc_co_u32_e32 v145, vcc, -1, v179, vcc
	v_add_co_u32_e32 v148, vcc, s8, v178
	s_mov_b32 s8, 0xfdff4000
	s_nop 0
	v_addc_co_u32_e32 v149, vcc, -1, v179, vcc
	v_add_co_u32_e32 v152, vcc, s8, v178
	s_mov_b32 s8, 0xfdff8000
	s_nop 0
	v_addc_co_u32_e32 v153, vcc, -1, v179, vcc
	v_add_co_u32_e32 v156, vcc, s8, v178
	global_load_dwordx4 v[144:147], v[144:145], off
	s_nop 0
	global_load_dwordx4 v[148:151], v[148:149], off
	v_addc_co_u32_e32 v157, vcc, -1, v179, vcc
	global_load_dwordx4 v[152:155], v[152:153], off
	s_nop 0
	global_load_dwordx4 v[156:159], v[156:157], off
	ds_read_b64_tr_b16 v[204:205], v184 offset:0
	ds_read_b64_tr_b16 v[206:207], v184 offset:0x800
	ds_read_b64_tr_b16 v[208:209], v184 offset:0x1000
	ds_read_b64_tr_b16 v[210:211], v184 offset:0x1800
	ds_read_b64_tr_b16 v[212:213], v184 offset:0x2000
	ds_read_b64_tr_b16 v[214:215], v184 offset:0x2800
	ds_read_b64_tr_b16 v[216:217], v184 offset:0x3000
	ds_read_b64_tr_b16 v[218:219], v184 offset:0x3800
	s_waitcnt lgkmcnt(0)
; #define SBAR() __builtin_amdgcn_sched_barrier(0)
; template <bool BAND>
; __device__ __forceinline__ void partialSM(f32x16& p0, f32x16& p1, float& m_reg, float& mn, float& alpha, int drel) {
;   constexpr float C = SCALE * 1.4426950408889634f;
;   if constexpr (BAND) {
; #pragma unroll
;     for (int r = 0; r < 16; ++r) {
;       int d = drel + (r & 3) + 8 * (r >> 2);
;       if ((unsigned)(d + 128) > 256u) p0[r] = -INFINITY;
;       if ((unsigned)(d + 32 + 128) > 256u) p1[r] = -INFINITY;
;     }
;   }
;   float pmax = p0[0];
; #pragma unroll
;   for (int r = 1; r < 16; ++r) pmax = fmaxf(pmax, p0[r]);
; #pragma unroll
;   for (int r = 0; r < 16; ++r) pmax = fmaxf(pmax, p1[r]);
;   { auto rr = __builtin_amdgcn_permlane32_swap(__float_as_uint(pmax), __float_as_uint(pmax), false, false);
;     pmax = fmaxf(__uint_as_float(rr[0]), __uint_as_float(rr[1])); }
;   if (__builtin_expect(__all(pmax - m_reg <= THR / SCALE), 1)) { mn = m_reg; alpha = 1.f; }
;   else { mn = fmaxf(m_reg, pmax); alpha = __builtin_amdgcn_exp2f((m_reg - mn) * C); m_reg = mn; }
;   float mnC = -mn * C;
; #pragma unroll
;   for (int r = 0; r < 16; ++r) p0[r] = fmaf(p0[r], C, mnC);
; #pragma unroll
;   for (int r = 0; r < 16; ++r) p1[r] = fmaf(p1[r], C, mnC);
; #pragma unroll
;   for (int r = 0; r < 16; ++r) p0[r] = __builtin_amdgcn_exp2f(p0[r]);
; }
; template <int D0> __device__ __forceinline__ void pv_one(f32x16& od, int vb, bf16x8 pa0, bf16x8 pa1, bf16x8 pa2, bf16x8 pa3) {
;   const s16x4 l0 = tr_read<v_rd_off(D0, 0, 0)>(vb), h0 = tr_read<v_rd_off(D0, 0, 1)>(vb), l1 = tr_read<v_rd_off(D0, 1, 0)>(vb), h1 = tr_read<v_rd_off(D0, 1, 1)>(vb);
;   const s16x4 l2 = tr_read<v_rd_off(D0, 2, 0)>(vb), h2 = tr_read<v_rd_off(D0, 2, 1)>(vb), l3 = tr_read<v_rd_off(D0, 3, 0)>(vb), h3 = tr_read<v_rd_off(D0, 3, 1)>(vb);
;   asm volatile("s_waitcnt lgkmcnt(0)" ::: "memory"); SBAR();
;     ...
;   od = __builtin_amdgcn_mfma_f32_32x32x16_bf16(pa0, PK(l0, h0), od, 0, 0, 0);
;   od = __builtin_amdgcn_mfma_f32_32x32x16_bf16(pa1, PK(l1, h1), od, 0, 0, 0);
;   od = __builtin_amdgcn_mfma_f32_32x32x16_bf16(pa2, PK(l2, h2), od, 0, 0, 0);
;   od = __builtin_amdgcn_mfma_f32_32x32x16_bf16(pa3, PK(l3, h3), od, 0, 0, 0);
;     ...
; }
; __device__ __forceinline__ void pv_d0(f32x16* o, int vb, bf16x8 pa0, bf16x8 pa1, bf16x8 pa2, bf16x8 pa3) {
	s_nop 0
	v_mfma_f32_32x32x16_bf16 v[0:15], v[160:163], v[204:207], v[0:15]
	v_max_f32_e32 v234, v81, v81
	v_max_f32_e32 v235, v80, v80
	v_max_f32_e32 v234, v235, v234
	v_max3_f32 v234, v234, v82, v83
	v_max3_f32 v234, v234, v84, v85
	v_max3_f32 v234, v234, v86, v87
	s_waitcnt vmcnt(4)
	ds_write_b128 v187, v[128:131] offset:32768
	ds_write_b128 v188, v[136:139] offset:32768
	ds_read_b64_tr_b16 v[204:205], v184 offset:0x200
	ds_read_b64_tr_b16 v[206:207], v184 offset:0xa00
	v_mfma_f32_32x32x16_bf16 v[0:15], v[164:167], v[208:211], v[0:15]
	v_max3_f32 v234, v234, v88, v89
	v_max3_f32 v234, v234, v90, v91
	v_max3_f32 v234, v234, v92, v93
	v_max3_f32 v234, v234, v94, v95
	v_max3_f32 v234, v234, v64, v65
	v_max3_f32 v234, v234, v66, v67
	ds_read_b64_tr_b16 v[208:209], v184 offset:0x1200
	ds_read_b64_tr_b16 v[210:211], v184 offset:0x1a00
	v_mfma_f32_32x32x16_bf16 v[0:15], v[170:173], v[212:215], v[0:15]
	v_max3_f32 v234, v234, v68, v69
	v_max3_f32 v234, v234, v70, v71
	v_max3_f32 v234, v234, v72, v73
	v_max3_f32 v234, v234, v74, v75
	v_max3_f32 v234, v234, v76, v77
	v_max3_f32 v234, v234, v78, v79
	ds_read_b64_tr_b16 v[212:213], v184 offset:0x2200
	ds_read_b64_tr_b16 v[214:215], v184 offset:0x2a00
	v_mfma_f32_32x32x16_bf16 v[0:15], v[200:203], v[216:219], v[0:15]
	v_mov_b32_e32 v235, v234
	s_nop 1
	v_permlane32_swap_b32_e32 v234, v235
	v_max_f32_e32 v235, v235, v235
	v_max_f32_e32 v234, v234, v234
	v_max_f32_e32 v234, v234, v235
	ds_read_b64_tr_b16 v[216:217], v184 offset:0x3200
	ds_read_b64_tr_b16 v[218:219], v184 offset:0x3a00
	s_waitcnt lgkmcnt(0)
	v_mfma_f32_32x32x16_bf16 v[48:63], v[160:163], v[204:207], v[48:63]
	v_sub_f32_e32 v235, v234, v168
	v_cmp_ge_f32_e32 vcc, s66, v235
	v_max_f32_e32 v235, v168, v168
	v_max_f32_e32 v234, v235, v234
	v_sub_f32_e32 v235, v168, v234
	v_mul_f32_e32 v235, 0x3e0293ee, v235
	ds_read_b64_tr_b16 v[204:205], v184 offset:0x400
	ds_read_b64_tr_b16 v[206:207], v184 offset:0xc00
	v_mfma_f32_32x32x16_bf16 v[48:63], v[164:167], v[208:211], v[48:63]
	v_exp_f32_e32 v235, v235
	s_cmp_eq_u64 vcc, exec
	s_cselect_b64 s[8:9], -1, 0
	s_nop 0
	v_cndmask_b32_e64 v236, v234, v168, s[8:9]
	v_mul_f32_e32 v237, 0xbe0293ee, v236
	ds_read_b64_tr_b16 v[208:209], v184 offset:0x1400
	ds_read_b64_tr_b16 v[210:211], v184 offset:0x1c00
	v_mfma_f32_32x32x16_bf16 v[48:63], v[170:173], v[212:215], v[48:63]
	ds_read_b64_tr_b16 v[212:213], v184 offset:0x2400
	ds_read_b64_tr_b16 v[214:215], v184 offset:0x2c00
	v_mfma_f32_32x32x16_bf16 v[48:63], v[200:203], v[216:219], v[48:63]
	v_fmamk_f32 v80, v80, 0x3e0293ee, v237
	v_fmamk_f32 v81, v81, 0x3e0293ee, v237
	v_fmamk_f32 v82, v82, 0x3e0293ee, v237
	v_fmamk_f32 v83, v83, 0x3e0293ee, v237
	ds_read_b64_tr_b16 v[216:217], v184 offset:0x3400
	ds_read_b64_tr_b16 v[218:219], v184 offset:0x3c00
	s_waitcnt lgkmcnt(0)
	v_mfma_f32_32x32x16_bf16 v[32:47], v[160:163], v[204:207], v[32:47]
	v_fmamk_f32 v84, v84, 0x3e0293ee, v237
	v_fmamk_f32 v85, v85, 0x3e0293ee, v237
	v_fmamk_f32 v86, v86, 0x3e0293ee, v237
	v_fmamk_f32 v87, v87, 0x3e0293ee, v237
	ds_read_b64_tr_b16 v[204:205], v184 offset:0x600
	ds_read_b64_tr_b16 v[206:207], v184 offset:0xe00
	v_mfma_f32_32x32x16_bf16 v[32:47], v[164:167], v[208:211], v[32:47]
	v_fmamk_f32 v88, v88, 0x3e0293ee, v237
	v_fmamk_f32 v89, v89, 0x3e0293ee, v237
	v_fmamk_f32 v90, v90, 0x3e0293ee, v237
	v_fmamk_f32 v91, v91, 0x3e0293ee, v237
	ds_read_b64_tr_b16 v[208:209], v184 offset:0x1600
	ds_read_b64_tr_b16 v[210:211], v184 offset:0x1e00
	v_mfma_f32_32x32x16_bf16 v[32:47], v[170:173], v[212:215], v[32:47]
	v_fmamk_f32 v92, v92, 0x3e0293ee, v237
	v_fmamk_f32 v93, v93, 0x3e0293ee, v237
	v_fmamk_f32 v94, v94, 0x3e0293ee, v237
	v_fmamk_f32 v95, v95, 0x3e0293ee, v237
	ds_read_b64_tr_b16 v[212:213], v184 offset:0x2600
	ds_read_b64_tr_b16 v[214:215], v184 offset:0x2e00
	v_mfma_f32_32x32x16_bf16 v[32:47], v[200:203], v[216:219], v[32:47]
	v_exp_f32_e32 v175, v81
	v_exp_f32_e32 v174, v83
	v_exp_f32_e32 v169, v93
	v_exp_f32_e32 v168, v95
	ds_read_b64_tr_b16 v[216:217], v184 offset:0x3600
	ds_read_b64_tr_b16 v[218:219], v184 offset:0x3e00
	s_waitcnt lgkmcnt(0)
	v_mfma_f32_32x32x16_bf16 v[16:31], v[160:163], v[204:207], v[16:31]
	v_exp_f32_e32 v160, v80
	v_exp_f32_e32 v161, v82
	v_exp_f32_e32 v162, v84
	v_exp_f32_e32 v163, v86
	v_fmamk_f32 v204, v69, 0x3e0293ee, v237
	v_fmamk_f32 v205, v70, 0x3e0293ee, v237
	v_fmamk_f32 v206, v71, 0x3e0293ee, v237
	v_fmamk_f32 v207, v72, 0x3e0293ee, v237
	v_mfma_f32_32x32x16_bf16 v[16:31], v[164:167], v[208:211], v[16:31]
	v_exp_f32_e32 v164, v88
	v_exp_f32_e32 v165, v90
	v_exp_f32_e32 v166, v92
	v_exp_f32_e32 v167, v94
	v_fmamk_f32 v208, v73, 0x3e0293ee, v237
	v_fmamk_f32 v209, v74, 0x3e0293ee, v237
	v_fmamk_f32 v210, v75, 0x3e0293ee, v237
	v_fmamk_f32 v211, v64, 0x3e0293ee, v237
	v_mfma_f32_32x32x16_bf16 v[16:31], v[170:173], v[212:215], v[16:31]
	v_exp_f32_e32 v173, v85
	v_exp_f32_e32 v172, v87
	v_exp_f32_e32 v171, v89
	v_exp_f32_e32 v170, v91
	v_fmamk_f32 v212, v65, 0x3e0293ee, v237
	v_fmamk_f32 v213, v66, 0x3e0293ee, v237
	v_fmamk_f32 v214, v67, 0x3e0293ee, v237
	v_fmamk_f32 v215, v68, 0x3e0293ee, v237
	v_mfma_f32_32x32x16_bf16 v[16:31], v[200:203], v[216:219], v[16:31]
	v_fmamk_f32 v203, v76, 0x3e0293ee, v237
	v_fmamk_f32 v216, v77, 0x3e0293ee, v237
	v_fmamk_f32 v217, v78, 0x3e0293ee, v237
	v_fmamk_f32 v202, v79, 0x3e0293ee, v237
	v_mov_b32_e32 v201, v236
	s_barrier
; #define SBAR() __builtin_amdgcn_sched_barrier(0)
; #define SLOAD(i, k0) do { sr_[i].vs0 = *reinterpret_cast<const bf16x8*>(&Vh[(long)((k0) + sr) * LDK + sc]); sr_[i].vs1 = *reinterpret_cast<const bf16x8*>(&Vh[(long)((k0) + 32 + sr) * LDK + sc]); \
;     sr_[i].ks0 = *reinterpret_cast<const bf16x8*>(&Kh[(long)((k0) + sr) * LDK + sc]); sr_[i].ks1 = *reinterpret_cast<const bf16x8*>(&Kh[(long)((k0) + 32 + sr) * LDK + sc]); } while (0)
; #define SWRITE(b, i) do { *(bf16x8*)((char*)V_lds + (b) * SHM_V + vst0) = sr_[i].vs0;          \
;     *(bf16x8*)((char*)V_lds + (b) * SHM_V + vst1) = sr_[i].vs1; int kc = sc * 2;               \
;     *(bf16x8*)((char*)K_lds + (b) * SHM_K + KSWZ(sr, kc)) = sr_[i].ks0;                       \
;     *(bf16x8*)((char*)K_lds + (b) * SHM_K + KSWZ(32 + sr, kc)) = sr_[i].ks1; } while (0)
; #define SWAIT() do { if constexpr (SDEPTH == 2) asm volatile("s_waitcnt vmcnt(4)" ::: "memory"); else asm volatile("s_waitcnt vmcnt(0)" ::: "memory"); } while (0)
; #define RESC(a) do { if (__any((a) < 1.f)) { if (hi == 0) al_l[r32] = (a); asm volatile("s_waitcnt lgkmcnt(0)" ::: "memory"); \
;     for (int d = 0; d < 4; ++d) for (int r = 0; r < 16; ++r) o[d][r] *= al_l[crow(r, hi)]; } } while (0)
; template <bool BAND>
; __device__ __forceinline__ void attn_body(const u16* Qb, const u16* __restrict__ Kh, const u16* __restrict__ Vh, u16* Ob, int NT, int kpos0, int qpos0, float sink_l2, char* lds, const float* __restrict__ qn) {
;     ...
;   f32x16 pA0, pA1, pB0, pB1; float mnA, mnB, alA, alB; bf16x8 pa0, pa1, pa2, pa3;
;   constexpr int SE = 0, SO = SDEPTH - 1;
;   SLOAD(SE, 0); asm volatile("s_waitcnt vmcnt(0)" ::: "memory"); SWRITE(0, SE); __syncthreads();
;   qkt(pA0, pA1, K_lds, qr, r32, hi); partialSM<BAND>(pA0, pA1, m_reg, mnA, alA, dq);
;   SLOAD(SO, KVBLK); if constexpr (SDEPTH == 2) { if (2 < NT) SLOAD(SE, 2 * KVBLK); }
;   SWAIT(); SWRITE(1, SO); __syncthreads();
;   for (int j = 1; j + 1 < NT; j += 2) {
;     SBAR(); qkt(pB0, pB1, (u16*)((char*)K_lds + SHM_K), qr, r32, hi);
;     finishSM(pA0, pA1, alA, l_reg, pa0, pa1, pa2, pa3); SBAR();
;     SLOAD(SO, (j + SDEPTH) * KVBLK); SBAR();
;     pv_d0(o, vb0, pa0, pa1, pa2, pa3); partialSM<BAND>(pB0, pB1, m_reg, mnB, alB, dq + j * KVBLK);
;     __syncthreads(); SWAIT(); SWRITE(0, SE);
;     RESC(alB); __syncthreads();
	s_waitcnt vmcnt(4)
	v_cndmask_b32_e64 v200, v235, 1.0, s[8:9]
	v_cmp_gt_f32_e32 vcc, 1.0, v200
	s_waitcnt vmcnt(4)
	ds_write_b128 v185, v[132:135]
	ds_write_b128 v186, v[140:143]
	s_cbranch_vccz .LBB0_1648
	s_and_saveexec_b64 s[18:19], s[6:7]
	ds_write_b32 v182, v200 offset:128
	s_or_b64 exec, exec, s[18:19]
	s_waitcnt lgkmcnt(0)
	ds_read_b128 v[128:131], v177 offset:224
	ds_read_b128 v[132:135], v177 offset:192
	ds_read_b128 v[136:139], v177 offset:160
	ds_read_b128 v[140:143], v177 offset:128
	s_waitcnt lgkmcnt(3)
	v_pk_mul_f32 v[14:15], v[14:15], v[130:131]
	s_waitcnt lgkmcnt(2)
	v_pk_mul_f32 v[10:11], v[10:11], v[134:135]
	s_waitcnt lgkmcnt(1)
	v_pk_mul_f32 v[6:7], v[6:7], v[138:139]
	s_waitcnt lgkmcnt(0)
	v_pk_mul_f32 v[2:3], v[2:3], v[142:143]
	v_pk_mul_f32 v[12:13], v[12:13], v[128:129]
	v_pk_mul_f32 v[8:9], v[8:9], v[132:133]
	v_pk_mul_f32 v[4:5], v[4:5], v[136:137]
	v_pk_mul_f32 v[0:1], v[0:1], v[140:141]
	v_pk_mul_f32 v[62:63], v[62:63], v[130:131]
	v_pk_mul_f32 v[58:59], v[58:59], v[134:135]
	v_pk_mul_f32 v[54:55], v[54:55], v[138:139]
	v_pk_mul_f32 v[50:51], v[50:51], v[142:143]
	v_pk_mul_f32 v[60:61], v[60:61], v[128:129]
	v_pk_mul_f32 v[56:57], v[56:57], v[132:133]
	v_pk_mul_f32 v[52:53], v[52:53], v[136:137]
	v_pk_mul_f32 v[48:49], v[48:49], v[140:141]
	v_pk_mul_f32 v[46:47], v[46:47], v[130:131]
	v_pk_mul_f32 v[42:43], v[42:43], v[134:135]
	v_pk_mul_f32 v[38:39], v[38:39], v[138:139]
	v_pk_mul_f32 v[34:35], v[34:35], v[142:143]
	v_pk_mul_f32 v[44:45], v[44:45], v[128:129]
	v_pk_mul_f32 v[40:41], v[40:41], v[132:133]
	v_pk_mul_f32 v[36:37], v[36:37], v[136:137]
	v_pk_mul_f32 v[32:33], v[32:33], v[140:141]
	v_pk_mul_f32 v[30:31], v[30:31], v[130:131]
	v_pk_mul_f32 v[26:27], v[26:27], v[134:135]
	v_pk_mul_f32 v[22:23], v[22:23], v[138:139]
	v_pk_mul_f32 v[18:19], v[18:19], v[142:143]
	v_pk_mul_f32 v[28:29], v[28:29], v[128:129]
	v_pk_mul_f32 v[24:25], v[24:25], v[132:133]
	v_pk_mul_f32 v[20:21], v[20:21], v[136:137]
	v_pk_mul_f32 v[16:17], v[16:17], v[140:141]

; #define SBAR() __builtin_amdgcn_sched_barrier(0)
; #define SLOAD(i, k0) do { sr_[i].vs0 = *reinterpret_cast<const bf16x8*>(&Vh[(long)((k0) + sr) * LDK + sc]); sr_[i].vs1 = *reinterpret_cast<const bf16x8*>(&Vh[(long)((k0) + 32 + sr) * LDK + sc]); \
;     sr_[i].ks0 = *reinterpret_cast<const bf16x8*>(&Kh[(long)((k0) + sr) * LDK + sc]); sr_[i].ks1 = *reinterpret_cast<const bf16x8*>(&Kh[(long)((k0) + 32 + sr) * LDK + sc]); } while (0)
; template <bool BAND>
; __device__ __forceinline__ void partialSM(f32x16& p0, f32x16& p1, float& m_reg, float& mn, float& alpha, int drel) {
;     ...
;   for (int r = 0; r < 16; ++r) p0[r] = fmaf(p0[r], C, mnC);
; #pragma unroll
;   for (int r = 0; r < 16; ++r) p1[r] = fmaf(p1[r], C, mnC);
; #pragma unroll
;   for (int r = 0; r < 16; ++r) p0[r] = __builtin_amdgcn_exp2f(p0[r]);
; }
; __device__ __forceinline__ void finishSM(f32x16& p0, f32x16& p1, float alpha, float& l_reg, bf16x8& pa0, bf16x8& pa1, bf16x8& pa2, bf16x8& pa3) {
; #pragma unroll
;   for (int r = 0; r < 16; ++r) p1[r] = __builtin_amdgcn_exp2f(p1[r]);
;   float ps = 0;
; #pragma unroll
;   for (int r = 0; r < 16; ++r) ps += p0[r];
; #pragma unroll
;   for (int r = 0; r < 16; ++r) ps += p1[r];
;   { auto rr = __builtin_amdgcn_permlane32_swap(__float_as_uint(ps), __float_as_uint(ps), false, false);
;     ps = __uint_as_float(rr[0]) + __uint_as_float(rr[1]); }
;   l_reg = l_reg * alpha + ps;
; template <bool BAND>
; __device__ __forceinline__ void attn_body(const u16* Qb, const u16* __restrict__ Kh, const u16* __restrict__ Vh, u16* Ob, int NT, int kpos0, int qpos0, float sink_l2, char* lds, const float* __restrict__ qn) {
;     ...
;     SBAR(); qkt(pA0, pA1, K_lds, qr, r32, hi);
;     finishSM(pB0, pB1, alB, l_reg, pa0, pa1, pa2, pa3); SBAR();
;     if (SDEPTH == 1 || j + 3 < NT) SLOAD(SE, (j + 1 + SDEPTH) * KVBLK); SBAR();
;     pv_d0(o, vb0 + (int)SHM_V, pa0, pa1, pa2, pa3); partialSM<BAND>(pA0, pA1, m_reg, mnA, alA, dq + (j + 1) * KVBLK);
;     __syncthreads(); SWAIT(); SWRITE(1, SO);
;     RESC(alA); __syncthreads();
;   }
;   SBAR(); qkt(pB0, pB1, (u16*)((char*)K_lds + SHM_K), qr, r32, hi);
;   finishSM(pA0, pA1, alA, l_reg, pa0, pa1, pa2, pa3); SBAR();
;   pv_d0(o, vb0, pa0, pa1, pa2, pa3); partialSM<BAND>(pB0, pB1, m_reg, mnB, alB, dq + (NT - 1) * KVBLK);
.LBB0_1654:
	v_mul_f32_e32 v146, 0xbe0293ee, v168
	v_mov_b32_e32 v147, v146
	s_mov_b32 s8, 0x3e0293ee
	v_pk_fma_f32 v[158:159], v[64:65], s[8:9], v[146:147] op_sel_hi:[1,0,0]
	v_add_f32_e32 v64, v198, v199
	v_pk_fma_f32 v[156:157], v[66:67], s[8:9], v[146:147] op_sel_hi:[1,0,0]
	v_pk_fma_f32 v[152:153], v[68:69], s[8:9], v[146:147] op_sel_hi:[1,0,0]
	v_pk_fma_f32 v[148:149], v[70:71], s[8:9], v[146:147] op_sel_hi:[1,0,0]
	v_pk_fma_f32 v[144:145], v[72:73], s[8:9], v[146:147] op_sel_hi:[1,0,0]
	v_pk_fma_f32 v[154:155], v[74:75], s[8:9], v[146:147] op_sel_hi:[1,0,0]
	v_pk_fma_f32 v[150:151], v[76:77], s[8:9], v[146:147] op_sel_hi:[1,0,0]
	v_pk_fma_f32 v[146:147], v[78:79], s[8:9], v[146:147] op_sel_hi:[1,0,0]
	v_fmac_f32_e32 v64, v197, v180
	v_add_f32_e32 v180, v202, v203
	s_add_i32 s21, s21, 2
	s_mov_b64 s[8:9], 0x10000
	v_fmac_f32_e32 v180, v64, v200
	s_cmp_ge_u32 s21, s22
	v_lshl_add_u64 v[178:179], v[178:179], 0, s[8:9]
	s_waitcnt lgkmcnt(0)
	s_cbranch_scc1 .Lmy_att_exit
	v_mov_b32_e32 v197, v160
	s_branch .LBB0_1644
.Lmy_att_exit:
	s_barrier
.LBB0_1656:
	ds_read_b128 v[64:67], v189 offset:49152
	ds_read_b128 v[68:71], v189 offset:57344
	s_waitcnt lgkmcnt(1)
	v_mfma_f32_32x32x16_bf16 v[80:95], v[64:67], v[124:127], 0
	s_waitcnt lgkmcnt(0)
	v_mfma_f32_32x32x16_bf16 v[64:79], v[68:71], v[124:127], 0
	ds_read_b128 v[124:127], v192 offset:49152
	ds_read_b128 v[128:131], v192 offset:57344
	s_waitcnt lgkmcnt(1)
	v_mfma_f32_32x32x16_bf16 v[80:95], v[124:127], v[120:123], v[80:95]
	s_waitcnt lgkmcnt(0)
	v_mfma_f32_32x32x16_bf16 v[64:79], v[128:131], v[120:123], v[64:79]
	ds_read_b128 v[120:123], v193 offset:49152
	ds_read_b128 v[124:127], v193 offset:57344
	s_waitcnt lgkmcnt(1)
	v_mfma_f32_32x32x16_bf16 v[80:95], v[120:123], v[116:119], v[80:95]
	s_waitcnt lgkmcnt(0)
	v_mfma_f32_32x32x16_bf16 v[64:79], v[124:127], v[116:119], v[64:79]
	ds_read_b128 v[116:119], v190 offset:49152
	ds_read_b128 v[120:123], v190 offset:57344
	s_waitcnt lgkmcnt(1)
	v_mfma_f32_32x32x16_bf16 v[80:95], v[116:119], v[112:115], v[80:95]
	s_waitcnt lgkmcnt(0)
	v_mfma_f32_32x32x16_bf16 v[64:79], v[120:123], v[112:115], v[64:79]
	ds_read_b128 v[112:115], v191 offset:49152
	ds_read_b128 v[116:119], v191 offset:57344
	v_exp_f32_e32 v120, v146
	v_exp_f32_e32 v121, v147
	s_waitcnt lgkmcnt(1)
	v_mfma_f32_32x32x16_bf16 v[80:95], v[112:115], v[108:111], v[80:95]
	s_waitcnt lgkmcnt(0)
	v_mfma_f32_32x32x16_bf16 v[64:79], v[116:119], v[108:111], v[64:79]
	ds_read_b128 v[108:111], v194 offset:49152
	ds_read_b128 v[112:115], v194 offset:57344
	v_exp_f32_e32 v116, v154
	v_exp_f32_e32 v117, v155
	v_exp_f32_e32 v118, v150
	v_exp_f32_e32 v119, v151
	s_waitcnt lgkmcnt(1)
	v_mfma_f32_32x32x16_bf16 v[80:95], v[108:111], v[104:107], v[80:95]
	s_waitcnt lgkmcnt(0)
	v_mfma_f32_32x32x16_bf16 v[64:79], v[112:115], v[104:107], v[64:79]
	ds_read_b128 v[104:107], v195 offset:49152
	ds_read_b128 v[108:111], v195 offset:57344
	v_exp_f32_e32 v112, v148
	v_exp_f32_e32 v113, v149
	v_exp_f32_e32 v114, v144
	v_exp_f32_e32 v115, v145
	s_waitcnt lgkmcnt(1)
	v_mfma_f32_32x32x16_bf16 v[80:95], v[104:107], v[100:103], v[80:95]
	s_waitcnt lgkmcnt(0)
	v_mfma_f32_32x32x16_bf16 v[64:79], v[108:111], v[100:103], v[64:79]
	ds_read_b128 v[100:103], v196 offset:49152
	ds_read_b128 v[104:107], v196 offset:57344
	v_exp_f32_e32 v108, v156
	v_exp_f32_e32 v109, v157
	v_exp_f32_e32 v110, v152
	v_exp_f32_e32 v111, v153
	s_waitcnt lgkmcnt(1)
	v_mfma_f32_32x32x16_bf16 v[80:95], v[100:103], v[96:99], v[80:95]
	s_waitcnt lgkmcnt(0)
	v_mfma_f32_32x32x16_bf16 v[64:79], v[104:107], v[96:99], v[64:79]
	v_add_f32_e32 v96, 0, v161
	v_add_f32_e32 v96, v175, v96
	v_add_f32_e32 v96, v162, v96
	v_add_f32_e32 v96, v201, v96
	v_add_f32_e32 v96, v174, v96
	v_add_f32_e32 v96, v204, v96
	v_add_f32_e32 v96, v163, v96
	v_add_f32_e32 v96, v173, v96
	v_add_f32_e32 v96, v164, v96
	v_add_f32_e32 v96, v171, v96
	v_add_f32_e32 v96, v165, v96
	v_add_f32_e32 v96, v172, v96
	v_exp_f32_e32 v106, v158
	v_add_f32_e32 v96, v166, v96
	v_exp_f32_e32 v107, v159
	v_add_f32_e32 v96, v169, v96
	v_add_f32_e32 v96, v167, v96
	v_add_f32_e32 v96, v170, v96
	v_add_f32_e32 v96, v106, v96
	v_add_f32_e32 v96, v107, v96
	v_add_f32_e32 v96, v108, v96
	v_add_f32_e32 v96, v109, v96
	v_add_f32_e32 v96, v110, v96
	v_add_f32_e32 v96, v111, v96
	v_add_f32_e32 v96, v112, v96
	v_add_f32_e32 v96, v113, v96
	v_add_f32_e32 v96, v114, v96
	v_add_f32_e32 v96, v115, v96
	v_add_f32_e32 v96, v116, v96
	v_add_f32_e32 v96, v117, v96
	v_add_f32_e32 v96, v118, v96
	v_add_f32_e32 v96, v119, v96
	v_add_f32_e32 v96, v120, v96
	v_add_f32_e32 v100, v121, v96
	v_mov_b32_e32 v101, v100
	v_cvt_pk_bf16_f32 v96, v161, v175
	v_cvt_pk_bf16_f32 v97, v162, v201
	v_cvt_pk_bf16_f32 v98, v174, v204
	v_cvt_pk_bf16_f32 v99, v163, v173
	s_nop 1
	v_permlane32_swap_b32_e32 v100, v101
	v_permlane32_swap_b32_e32 v96, v98
	v_permlane32_swap_b32_e32 v97, v99
	v_cvt_pk_bf16_f32 v102, v164, v171
	v_cvt_pk_bf16_f32 v103, v165, v172
	v_cvt_pk_bf16_f32 v104, v166, v169
	v_cvt_pk_bf16_f32 v105, v167, v170
	v_cvt_pk_bf16_f32 v106, v106, v107
	v_cvt_pk_bf16_f32 v107, v108, v109
	v_cvt_pk_bf16_f32 v108, v110, v111
	v_cvt_pk_bf16_f32 v109, v112, v113
	v_cvt_pk_bf16_f32 v110, v114, v115
	v_cvt_pk_bf16_f32 v111, v116, v117
	v_cvt_pk_bf16_f32 v112, v118, v119
	v_cvt_pk_bf16_f32 v113, v120, v121
	s_nop 0
	v_permlane32_swap_b32_e32 v102, v104
	v_permlane32_swap_b32_e32 v103, v105
	v_permlane32_swap_b32_e32 v106, v108
	v_permlane32_swap_b32_e32 v107, v109
	v_permlane32_swap_b32_e32 v110, v112
	v_permlane32_swap_b32_e32 v111, v113
	ds_read_b64_tr_b16 v[114:115], v184 offset:0
	ds_read_b64_tr_b16 v[116:117], v184 offset:0x800
	ds_read_b64_tr_b16 v[118:119], v184 offset:0x1000
	ds_read_b64_tr_b16 v[120:121], v184 offset:0x1800
	ds_read_b64_tr_b16 v[122:123], v184 offset:0x2000
	ds_read_b64_tr_b16 v[124:125], v184 offset:0x2800
	ds_read_b64_tr_b16 v[126:127], v184 offset:0x3000
	ds_read_b64_tr_b16 v[128:129], v184 offset:0x3800
	s_waitcnt lgkmcnt(0)
; #define SBAR() __builtin_amdgcn_sched_barrier(0)
; template <int D0> __device__ __forceinline__ void pv_one(f32x16& od, int vb, bf16x8 pa0, bf16x8 pa1, bf16x8 pa2, bf16x8 pa3) {
;   const s16x4 l0 = tr_read<v_rd_off(D0, 0, 0)>(vb), h0 = tr_read<v_rd_off(D0, 0, 1)>(vb), l1 = tr_read<v_rd_off(D0, 1, 0)>(vb), h1 = tr_read<v_rd_off(D0, 1, 1)>(vb);
;   const s16x4 l2 = tr_read<v_rd_off(D0, 2, 0)>(vb), h2 = tr_read<v_rd_off(D0, 2, 1)>(vb), l3 = tr_read<v_rd_off(D0, 3, 0)>(vb), h3 = tr_read<v_rd_off(D0, 3, 1)>(vb);
;   asm volatile("s_waitcnt lgkmcnt(0)" ::: "memory"); SBAR();
;     ...
;   od = __builtin_amdgcn_mfma_f32_32x32x16_bf16(pa0, PK(l0, h0), od, 0, 0, 0);
;   od = __builtin_amdgcn_mfma_f32_32x32x16_bf16(pa1, PK(l1, h1), od, 0, 0, 0);
;   od = __builtin_amdgcn_mfma_f32_32x32x16_bf16(pa2, PK(l2, h2), od, 0, 0, 0);
;   od = __builtin_amdgcn_mfma_f32_32x32x16_bf16(pa3, PK(l3, h3), od, 0, 0, 0);
;     ...
; }
; __device__ __forceinline__ void pv_d0(f32x16* o, int vb, bf16x8 pa0, bf16x8 pa1, bf16x8 pa2, bf16x8 pa3) {
;   pv_one<0>(o[0], vb, pa0, pa1, pa2, pa3); pv_one<1>(o[1], vb, pa0, pa1, pa2, pa3); pv_one<2>(o[2], vb, pa0, pa1, pa2, pa3); pv_one<3>(o[3], vb, pa0, pa1, pa2, pa3);
; }
; template <bool BAND>
; __device__ __forceinline__ void attn_body(const u16* Qb, const u16* __restrict__ Kh, const u16* __restrict__ Vh, u16* Ob, int NT, int kpos0, int qpos0, float sink_l2, char* lds, const float* __restrict__ qn) {
;     ...
;   f32x16 pA0, pA1, pB0, pB1; float mnA, mnB, alA, alB; bf16x8 pa0, pa1, pa2, pa3;
;   constexpr int SE = 0, SO = SDEPTH - 1;
;   SLOAD(SE, 0); asm volatile("s_waitcnt vmcnt(0)" ::: "memory"); SWRITE(0, SE); __syncthreads();
;   qkt(pA0, pA1, K_lds, qr, r32, hi); partialSM<BAND>(pA0, pA1, m_reg, mnA, alA, dq);
;   SLOAD(SO, KVBLK); if constexpr (SDEPTH == 2) { if (2 < NT) SLOAD(SE, 2 * KVBLK); }
;   SWAIT(); SWRITE(1, SO); __syncthreads();
;   for (int j = 1; j + 1 < NT; j += 2) {
;     SBAR(); qkt(pB0, pB1, (u16*)((char*)K_lds + SHM_K), qr, r32, hi);
;     finishSM(pA0, pA1, alA, l_reg, pa0, pa1, pa2, pa3); SBAR();
;     SLOAD(SO, (j + SDEPTH) * KVBLK); SBAR();
;     pv_d0(o, vb0, pa0, pa1, pa2, pa3); partialSM<BAND>(pB0, pB1, m_reg, mnB, alB, dq + j * KVBLK);
;     __syncthreads(); SWAIT(); SWRITE(0, SE);
;     RESC(alB); __syncthreads();
;     SBAR(); qkt(pA0, pA1, K_lds, qr, r32, hi);
;     finishSM(pB0, pB1, alB, l_reg, pa0, pa1, pa2, pa3); SBAR();
	s_nop 0
	v_mfma_f32_32x32x16_bf16 v[0:15], v[96:99], v[114:117], v[0:15]
	ds_read_b64_tr_b16 v[114:115], v184 offset:0x200
	ds_read_b64_tr_b16 v[116:117], v184 offset:0xa00
	v_mfma_f32_32x32x16_bf16 v[0:15], v[102:105], v[118:121], v[0:15]
	ds_read_b64_tr_b16 v[118:119], v184 offset:0x1200
	ds_read_b64_tr_b16 v[120:121], v184 offset:0x1a00
	v_mfma_f32_32x32x16_bf16 v[0:15], v[106:109], v[122:125], v[0:15]
	ds_read_b64_tr_b16 v[122:123], v184 offset:0x2200
	ds_read_b64_tr_b16 v[124:125], v184 offset:0x2a00
	v_mfma_f32_32x32x16_bf16 v[0:15], v[110:113], v[126:129], v[0:15]
	ds_read_b64_tr_b16 v[126:127], v184 offset:0x3200
	ds_read_b64_tr_b16 v[128:129], v184 offset:0x3a00
	s_waitcnt lgkmcnt(0)
	v_mfma_f32_32x32x16_bf16 v[48:63], v[96:99], v[114:117], v[48:63]
	ds_read_b64_tr_b16 v[114:115], v184 offset:0x400
	ds_read_b64_tr_b16 v[116:117], v184 offset:0xc00
	v_mfma_f32_32x32x16_bf16 v[48:63], v[102:105], v[118:121], v[48:63]
	ds_read_b64_tr_b16 v[118:119], v184 offset:0x1400
	ds_read_b64_tr_b16 v[120:121], v184 offset:0x1c00
	v_mfma_f32_32x32x16_bf16 v[48:63], v[106:109], v[122:125], v[48:63]
	ds_read_b64_tr_b16 v[122:123], v184 offset:0x2400
	ds_read_b64_tr_b16 v[124:125], v184 offset:0x2c00
	v_mfma_f32_32x32x16_bf16 v[48:63], v[110:113], v[126:129], v[48:63]
	ds_read_b64_tr_b16 v[126:127], v184 offset:0x3400
	ds_read_b64_tr_b16 v[128:129], v184 offset:0x3c00
	s_waitcnt lgkmcnt(0)
	v_mfma_f32_32x32x16_bf16 v[32:47], v[96:99], v[114:117], v[32:47]
	ds_read_b64_tr_b16 v[114:115], v184 offset:0x600
	ds_read_b64_tr_b16 v[116:117], v184 offset:0xe00
	v_mfma_f32_32x32x16_bf16 v[32:47], v[102:105], v[118:121], v[32:47]
	ds_read_b64_tr_b16 v[118:119], v184 offset:0x1600
	ds_read_b64_tr_b16 v[120:121], v184 offset:0x1e00
	v_mfma_f32_32x32x16_bf16 v[32:47], v[106:109], v[122:125], v[32:47]
	ds_read_b64_tr_b16 v[122:123], v184 offset:0x2600
	ds_read_b64_tr_b16 v[124:125], v184 offset:0x2e00
	v_mfma_f32_32x32x16_bf16 v[32:47], v[110:113], v[126:129], v[32:47]
	ds_read_b64_tr_b16 v[126:127], v184 offset:0x3600
	ds_read_b64_tr_b16 v[128:129], v184 offset:0x3e00
	s_waitcnt lgkmcnt(0)
	v_mfma_f32_32x32x16_bf16 v[16:31], v[96:99], v[114:117], v[16:31]
	v_max_f32_e32 v96, v81, v81
	v_max_f32_e32 v97, v80, v80
	v_max_f32_e32 v96, v97, v96
	v_max3_f32 v96, v96, v82, v83
	v_max3_f32 v96, v96, v84, v85
	v_max3_f32 v96, v96, v86, v87
	v_max3_f32 v96, v96, v88, v89
	v_max3_f32 v96, v96, v90, v91
	v_max3_f32 v96, v96, v92, v93
	v_mfma_f32_32x32x16_bf16 v[16:31], v[102:105], v[118:121], v[16:31]
	v_max3_f32 v96, v96, v94, v95
	v_max3_f32 v96, v96, v64, v65
	v_max3_f32 v96, v96, v66, v67
	v_max3_f32 v96, v96, v68, v69
	v_max3_f32 v96, v96, v70, v71
	v_max3_f32 v96, v96, v72, v73
	v_max3_f32 v96, v96, v74, v75
	v_max3_f32 v96, v96, v76, v77
	v_mfma_f32_32x32x16_bf16 v[16:31], v[106:109], v[122:125], v[16:31]
	v_max3_f32 v96, v96, v78, v79
	v_mov_b32_e32 v97, v96
	s_nop 1
	v_permlane32_swap_b32_e32 v96, v97
	v_max_f32_e32 v97, v97, v97
	v_max_f32_e32 v96, v96, v96
	v_max_f32_e32 v96, v96, v97
	v_sub_f32_e32 v97, v96, v168
	v_cmp_ge_f32_e32 vcc, s66, v97
	v_max_f32_e32 v97, v168, v168
	v_max_f32_e32 v97, v97, v96
	v_mfma_f32_32x32x16_bf16 v[16:31], v[110:113], v[126:129], v[16:31]
	v_sub_f32_e32 v96, v168, v97
	v_mul_f32_e32 v96, 0x3e0293ee, v96
	v_exp_f32_e32 v96, v96
	s_cmp_eq_u64 vcc, exec
	s_cselect_b64 s[8:9], -1, 0
	v_cndmask_b32_e64 v96, v96, 1.0, s[8:9]
	v_cmp_gt_f32_e32 vcc, 1.0, v96
	s_barrier
	s_cbranch_vccz .LBB0_1660
	s_and_saveexec_b64 s[18:19], s[6:7]
	ds_write_b32 v182, v96 offset:128
	s_or_b64 exec, exec, s[18:19]
	s_waitcnt lgkmcnt(0)
	ds_read_b128 v[102:105], v177 offset:224
	ds_read_b128 v[106:109], v177 offset:192
	ds_read_b128 v[110:113], v177 offset:160
	ds_read_b128 v[114:117], v177 offset:128
	s_waitcnt lgkmcnt(3)
	v_pk_mul_f32 v[14:15], v[14:15], v[104:105]
	s_waitcnt lgkmcnt(2)
	v_pk_mul_f32 v[10:11], v[10:11], v[108:109]
	s_waitcnt lgkmcnt(1)
	v_pk_mul_f32 v[6:7], v[6:7], v[112:113]
	s_waitcnt lgkmcnt(0)
	v_pk_mul_f32 v[2:3], v[2:3], v[116:117]
	v_pk_mul_f32 v[12:13], v[12:13], v[102:103]
	v_pk_mul_f32 v[8:9], v[8:9], v[106:107]
	v_pk_mul_f32 v[4:5], v[4:5], v[110:111]
	v_pk_mul_f32 v[0:1], v[0:1], v[114:115]
	v_pk_mul_f32 v[62:63], v[62:63], v[104:105]
	v_pk_mul_f32 v[58:59], v[58:59], v[108:109]
	v_pk_mul_f32 v[54:55], v[54:55], v[112:113]
	v_pk_mul_f32 v[50:51], v[50:51], v[116:117]
	v_pk_mul_f32 v[60:61], v[60:61], v[102:103]
	v_pk_mul_f32 v[56:57], v[56:57], v[106:107]
	v_pk_mul_f32 v[52:53], v[52:53], v[110:111]
	v_pk_mul_f32 v[48:49], v[48:49], v[114:115]
	v_pk_mul_f32 v[46:47], v[46:47], v[104:105]
	v_pk_mul_f32 v[42:43], v[42:43], v[108:109]
	v_pk_mul_f32 v[38:39], v[38:39], v[112:113]
	v_pk_mul_f32 v[34:35], v[34:35], v[116:117]
	v_pk_mul_f32 v[44:45], v[44:45], v[102:103]
	v_pk_mul_f32 v[40:41], v[40:41], v[106:107]
	v_pk_mul_f32 v[36:37], v[36:37], v[110:111]
	v_pk_mul_f32 v[32:33], v[32:33], v[114:115]
	v_pk_mul_f32 v[30:31], v[30:31], v[104:105]
	v_pk_mul_f32 v[26:27], v[26:27], v[108:109]
	v_pk_mul_f32 v[22:23], v[22:23], v[112:113]
	v_pk_mul_f32 v[18:19], v[18:19], v[116:117]
	v_pk_mul_f32 v[28:29], v[28:29], v[102:103]
	v_pk_mul_f32 v[24:25], v[24:25], v[106:107]
	v_pk_mul_f32 v[20:21], v[20:21], v[110:111]
	v_pk_mul_f32 v[16:17], v[16:17], v[114:115]
